# GEMM unit boundary: first two counted vmcnt waits of a unit skipped when the epilogue already drained the cross-unit prefetch (do not wait for the output stores to reach L2 before the first MFMA clust
# baseline (speedup 1.0000x reference)
.LBB0_344:
	s_add_i32 vcc_lo, s50, 2
	s_add_u32 s68, s48, 0x80
	s_addc_u32 s51, s49, 0
	s_add_i32 s70, 0, 0x10000
	s_cmp_eq_u32 s15, s50
	s_cselect_b32 s51, s1, s51
	s_cselect_b32 s50, s0, s68
	v_add_u32_e32 v0, s70, v223
	s_cselect_b32 s69, s53, s57
	s_cselect_b32 s68, s52, s56
	s_add_i32 s71, 0, 0x14000
	ds_read_b128 v[130:133], v0
	ds_read_b128 v[134:137], v0 offset:1024
	ds_read_b128 v[138:141], v0 offset:2048
	ds_read_b128 v[142:145], v0 offset:3072
	v_add_u32_e32 v0, s71, v223
	ds_read_b128 v[146:149], v0
	ds_read_b128 v[150:153], v0 offset:1024
	ds_read_b128 v[154:157], v0 offset:2048
	ds_read_b128 v[158:161], v0 offset:3072
	v_lshl_add_u64 v[212:213], s[48:49], 0, v[192:193]
	s_add_i32 m0, s67, 0xc000
	ds_read_b128 v[162:165], v226
	ds_read_b128 v[166:169], v226 offset:1024
	ds_read_b128 v[170:173], v226 offset:2048
	ds_read_b128 v[174:177], v226 offset:3072
	ds_read_b128 v[196:199], v226 offset:4096
	ds_read_b128 v[200:203], v226 offset:5120
	ds_read_b128 v[204:207], v226 offset:6144
	ds_read_b128 v[208:211], v226 offset:7168
	global_load_lds_dwordx4 v[212:213], off
	v_lshl_add_u64 v[212:213], s[48:49], 0, v[194:195]
	s_add_i32 m0, s67, 0xe000
	s_nop 0
	global_load_lds_dwordx4 v[212:213], off
	s_cmp_lg_u32 s100, 1
	s_cbranch_scc1 .Lws_waitA
	s_cmp_eq_u32 vcc_lo, 2
	s_cbranch_scc1 .Lws_skipA
.Lws_waitA:
	s_waitcnt vmcnt(8)
.Lws_skipA:
	s_waitcnt lgkmcnt(0)
	s_barrier
	s_setprio 1
	s_waitcnt lgkmcnt(0)
	v_mfma_f32_16x16x32_bf16 v[126:129], v[130:133], v[162:165], v[126:129]
	v_mfma_f32_16x16x32_bf16 v[122:125], v[138:141], v[162:165], v[122:125]
	v_mfma_f32_16x16x32_bf16 v[118:121], v[130:133], v[170:173], v[118:121]
	v_mfma_f32_16x16x32_bf16 v[114:117], v[138:141], v[170:173], v[114:117]
	v_mfma_f32_16x16x32_bf16 v[102:105], v[130:133], v[196:199], v[102:105]
	v_mfma_f32_16x16x32_bf16 v[98:101], v[138:141], v[196:199], v[98:101]
	v_mfma_f32_16x16x32_bf16 v[86:89], v[130:133], v[204:207], v[86:89]
	v_mfma_f32_16x16x32_bf16 v[82:85], v[138:141], v[204:207], v[82:85]
	v_mfma_f32_16x16x32_bf16 v[126:129], v[134:137], v[166:169], v[126:129]
	v_mfma_f32_16x16x32_bf16 v[122:125], v[142:145], v[166:169], v[122:125]
	v_mfma_f32_16x16x32_bf16 v[118:121], v[134:137], v[174:177], v[118:121]
	v_mfma_f32_16x16x32_bf16 v[114:117], v[142:145], v[174:177], v[114:117]
	v_mfma_f32_16x16x32_bf16 v[102:105], v[134:137], v[200:203], v[102:105]
	v_mfma_f32_16x16x32_bf16 v[98:101], v[142:145], v[200:203], v[98:101]
	v_mfma_f32_16x16x32_bf16 v[86:89], v[134:137], v[208:211], v[86:89]
	v_mfma_f32_16x16x32_bf16 v[82:85], v[142:145], v[208:211], v[82:85]
	s_setprio 0
	s_setprio 1
	v_mfma_f32_16x16x32_bf16 v[110:113], v[146:149], v[162:165], v[110:113]
	v_mfma_f32_16x16x32_bf16 v[106:109], v[154:157], v[162:165], v[106:109]
	v_mfma_f32_16x16x32_bf16 v[94:97], v[146:149], v[170:173], v[94:97]
	v_mfma_f32_16x16x32_bf16 v[90:93], v[154:157], v[170:173], v[90:93]
	v_mfma_f32_16x16x32_bf16 v[78:81], v[146:149], v[196:199], v[78:81]
	v_mfma_f32_16x16x32_bf16 v[74:77], v[154:157], v[196:199], v[74:77]
	v_mfma_f32_16x16x32_bf16 v[70:73], v[146:149], v[204:207], v[70:73]
	v_mfma_f32_16x16x32_bf16 v[66:69], v[154:157], v[204:207], v[66:69]
	v_mfma_f32_16x16x32_bf16 v[110:113], v[150:153], v[166:169], v[110:113]
	v_mfma_f32_16x16x32_bf16 v[106:109], v[158:161], v[166:169], v[106:109]
	v_mfma_f32_16x16x32_bf16 v[94:97], v[150:153], v[174:177], v[94:97]
	v_mfma_f32_16x16x32_bf16 v[90:93], v[158:161], v[174:177], v[90:93]
	v_mfma_f32_16x16x32_bf16 v[78:81], v[150:153], v[200:203], v[78:81]
	v_mfma_f32_16x16x32_bf16 v[74:77], v[158:161], v[200:203], v[74:77]
	v_mfma_f32_16x16x32_bf16 v[70:73], v[150:153], v[208:211], v[70:73]
	v_mfma_f32_16x16x32_bf16 v[66:69], v[158:161], v[208:211], v[66:69]
	s_setprio 0
	s_barrier
	s_add_i32 s70, s70, s63
	v_lshl_add_u64 v[212:213], s[68:69], 0, v[186:187]
	s_mov_b32 m0, s70
	ds_read_b128 v[162:165], v226 offset:16384
	ds_read_b128 v[166:169], v226 offset:17408
	ds_read_b128 v[170:173], v226 offset:18432
	ds_read_b128 v[174:177], v226 offset:19456
	ds_read_b128 v[196:199], v226 offset:20480
	ds_read_b128 v[200:203], v226 offset:21504
	ds_read_b128 v[204:207], v226 offset:22528
	ds_read_b128 v[208:211], v226 offset:23552
	global_load_lds_dwordx4 v[212:213], off
	s_add_i32 m0, s70, 0x2000
	v_lshl_add_u64 v[214:215], s[68:69], 0, v[182:183]
	s_add_u32 s68, s68, s90
	s_addc_u32 s69, s69, 0
	s_add_i32 s70, s71, s63
	global_load_lds_dwordx4 v[214:215], off
	v_lshl_add_u64 v[216:217], s[68:69], 0, v[186:187]
	s_mov_b32 m0, s70
	v_lshl_add_u64 v[218:219], s[68:69], 0, v[182:183]
	global_load_lds_dwordx4 v[216:217], off
	s_add_i32 m0, s70, 0x2000
	v_lshl_add_u64 v[232:233], s[50:51], 0, v[184:185]
	global_load_lds_dwordx4 v[218:219], off
	s_mov_b32 m0, s67
	v_lshl_add_u64 v[234:235], s[50:51], 0, v[180:181]
	global_load_lds_dwordx4 v[232:233], off
	s_mov_b32 m0, s33
	s_nop 0
	global_load_lds_dwordx4 v[234:235], off
	s_cmp_lg_u32 s100, 1
	s_cbranch_scc1 .Lws_waitB
	s_cmp_eq_u32 vcc_lo, 2
	s_cbranch_scc1 .Lws_skipB

.Lws_skipB:
	s_waitcnt lgkmcnt(0)
	s_barrier
	s_setprio 1
	s_waitcnt lgkmcnt(0)
	v_mfma_f32_16x16x32_bf16 v[62:65], v[130:133], v[162:165], v[62:65]
	v_mfma_f32_16x16x32_bf16 v[58:61], v[138:141], v[162:165], v[58:61]
	v_mfma_f32_16x16x32_bf16 v[54:57], v[130:133], v[170:173], v[54:57]
	v_mfma_f32_16x16x32_bf16 v[50:53], v[138:141], v[170:173], v[50:53]
	v_mfma_f32_16x16x32_bf16 v[38:41], v[130:133], v[196:199], v[38:41]
	v_mfma_f32_16x16x32_bf16 v[34:37], v[138:141], v[196:199], v[34:37]
	v_mfma_f32_16x16x32_bf16 v[22:25], v[130:133], v[204:207], v[22:25]
	v_mfma_f32_16x16x32_bf16 v[18:21], v[138:141], v[204:207], v[18:21]
	v_mfma_f32_16x16x32_bf16 v[62:65], v[134:137], v[166:169], v[62:65]
	v_mfma_f32_16x16x32_bf16 v[58:61], v[142:145], v[166:169], v[58:61]
	v_mfma_f32_16x16x32_bf16 v[54:57], v[134:137], v[174:177], v[54:57]
	v_mfma_f32_16x16x32_bf16 v[50:53], v[142:145], v[174:177], v[50:53]
	v_mfma_f32_16x16x32_bf16 v[38:41], v[134:137], v[200:203], v[38:41]
	v_mfma_f32_16x16x32_bf16 v[34:37], v[142:145], v[200:203], v[34:37]
	v_mfma_f32_16x16x32_bf16 v[22:25], v[134:137], v[208:211], v[22:25]
	v_mfma_f32_16x16x32_bf16 v[18:21], v[142:145], v[208:211], v[18:21]
	s_setprio 0
	s_setprio 1
	v_mfma_f32_16x16x32_bf16 v[46:49], v[146:149], v[162:165], v[46:49]
	v_mfma_f32_16x16x32_bf16 v[42:45], v[154:157], v[162:165], v[42:45]
	v_mfma_f32_16x16x32_bf16 v[30:33], v[146:149], v[170:173], v[30:33]
	v_mfma_f32_16x16x32_bf16 v[26:29], v[154:157], v[170:173], v[26:29]
	v_mfma_f32_16x16x32_bf16 v[14:17], v[146:149], v[196:199], v[14:17]
	v_mfma_f32_16x16x32_bf16 v[10:13], v[154:157], v[196:199], v[10:13]
	v_mfma_f32_16x16x32_bf16 v[6:9], v[146:149], v[204:207], v[6:9]
	v_mfma_f32_16x16x32_bf16 v[2:5], v[154:157], v[204:207], v[2:5]
	v_mfma_f32_16x16x32_bf16 v[46:49], v[150:153], v[166:169], v[46:49]
	v_mfma_f32_16x16x32_bf16 v[42:45], v[158:161], v[166:169], v[42:45]
	v_mfma_f32_16x16x32_bf16 v[30:33], v[150:153], v[174:177], v[30:33]
	v_mfma_f32_16x16x32_bf16 v[26:29], v[158:161], v[174:177], v[26:29]
	v_mfma_f32_16x16x32_bf16 v[14:17], v[150:153], v[200:203], v[14:17]
	v_mfma_f32_16x16x32_bf16 v[10:13], v[158:161], v[200:203], v[10:13]
	v_mfma_f32_16x16x32_bf16 v[6:9], v[150:153], v[208:211], v[6:9]
	v_mfma_f32_16x16x32_bf16 v[2:5], v[158:161], v[208:211], v[2:5]
	s_setprio 0
	s_barrier
	s_add_i32 s68, 0, 0x18000
	v_add_u32_e32 v0, s68, v223
	s_add_i32 s69, 0, 0x1c000
	ds_read_b128 v[130:133], v0
	ds_read_b128 v[134:137], v0 offset:1024
	ds_read_b128 v[138:141], v0 offset:2048
	ds_read_b128 v[142:145], v0 offset:3072
	v_add_u32_e32 v0, s69, v223
	ds_read_b128 v[146:149], v0
	ds_read_b128 v[150:153], v0 offset:1024
	ds_read_b128 v[154:157], v0 offset:2048
	ds_read_b128 v[158:161], v0 offset:3072
	s_add_u32 s50, s50, s90
	s_addc_u32 s51, s51, 0
	s_mov_b32 m0, s65
	v_lshl_add_u64 v[236:237], s[50:51], 0, v[184:185]
	ds_read_b128 v[162:165], v226 offset:32768
	ds_read_b128 v[166:169], v226 offset:33792
	ds_read_b128 v[170:173], v226 offset:34816
	ds_read_b128 v[174:177], v226 offset:35840
	ds_read_b128 v[196:199], v226 offset:36864
	ds_read_b128 v[200:203], v226 offset:37888
	ds_read_b128 v[204:207], v226 offset:38912
	ds_read_b128 v[208:211], v226 offset:39936
	global_load_lds_dwordx4 v[236:237], off
	v_lshl_add_u64 v[236:237], s[50:51], 0, v[180:181]
	s_mov_b32 m0, s22
	s_nop 0
	global_load_lds_dwordx4 v[236:237], off
	s_waitcnt vmcnt(8)
	s_waitcnt lgkmcnt(0)
	s_barrier
	s_setprio 1
	s_waitcnt lgkmcnt(0)
	v_mfma_f32_16x16x32_bf16 v[126:129], v[130:133], v[162:165], v[126:129]
	v_mfma_f32_16x16x32_bf16 v[122:125], v[138:141], v[162:165], v[122:125]
	v_mfma_f32_16x16x32_bf16 v[118:121], v[130:133], v[170:173], v[118:121]
	v_mfma_f32_16x16x32_bf16 v[114:117], v[138:141], v[170:173], v[114:117]
	v_mfma_f32_16x16x32_bf16 v[102:105], v[130:133], v[196:199], v[102:105]
	v_mfma_f32_16x16x32_bf16 v[98:101], v[138:141], v[196:199], v[98:101]
	v_mfma_f32_16x16x32_bf16 v[86:89], v[130:133], v[204:207], v[86:89]
	v_mfma_f32_16x16x32_bf16 v[82:85], v[138:141], v[204:207], v[82:85]
	v_mfma_f32_16x16x32_bf16 v[126:129], v[134:137], v[166:169], v[126:129]
	v_mfma_f32_16x16x32_bf16 v[122:125], v[142:145], v[166:169], v[122:125]
	v_mfma_f32_16x16x32_bf16 v[118:121], v[134:137], v[174:177], v[118:121]
	v_mfma_f32_16x16x32_bf16 v[114:117], v[142:145], v[174:177], v[114:117]
	v_mfma_f32_16x16x32_bf16 v[102:105], v[134:137], v[200:203], v[102:105]
	v_mfma_f32_16x16x32_bf16 v[98:101], v[142:145], v[200:203], v[98:101]
	v_mfma_f32_16x16x32_bf16 v[86:89], v[134:137], v[208:211], v[86:89]
	v_mfma_f32_16x16x32_bf16 v[82:85], v[142:145], v[208:211], v[82:85]
	s_setprio 0
	s_setprio 1
	v_mfma_f32_16x16x32_bf16 v[110:113], v[146:149], v[162:165], v[110:113]
	v_mfma_f32_16x16x32_bf16 v[106:109], v[154:157], v[162:165], v[106:109]
	v_mfma_f32_16x16x32_bf16 v[94:97], v[146:149], v[170:173], v[94:97]
	v_mfma_f32_16x16x32_bf16 v[90:93], v[154:157], v[170:173], v[90:93]
	v_mfma_f32_16x16x32_bf16 v[78:81], v[146:149], v[196:199], v[78:81]
	v_mfma_f32_16x16x32_bf16 v[74:77], v[154:157], v[196:199], v[74:77]
	v_mfma_f32_16x16x32_bf16 v[70:73], v[146:149], v[204:207], v[70:73]
	v_mfma_f32_16x16x32_bf16 v[66:69], v[154:157], v[204:207], v[66:69]
	v_mfma_f32_16x16x32_bf16 v[110:113], v[150:153], v[166:169], v[110:113]
	v_mfma_f32_16x16x32_bf16 v[106:109], v[158:161], v[166:169], v[106:109]
	v_mfma_f32_16x16x32_bf16 v[94:97], v[150:153], v[174:177], v[94:97]
	v_mfma_f32_16x16x32_bf16 v[90:93], v[158:161], v[174:177], v[90:93]
	v_mfma_f32_16x16x32_bf16 v[78:81], v[150:153], v[200:203], v[78:81]
	v_mfma_f32_16x16x32_bf16 v[74:77], v[158:161], v[200:203], v[74:77]
	v_mfma_f32_16x16x32_bf16 v[70:73], v[150:153], v[208:211], v[70:73]
	v_mfma_f32_16x16x32_bf16 v[66:69], v[158:161], v[208:211], v[66:69]
	s_setprio 0
	s_barrier
	s_add_i32 s50, s68, s63
	v_lshl_add_u64 v[212:213], v[212:213], 0, s[94:95]
	s_mov_b32 m0, s50
	ds_read_b128 v[162:165], v226 offset:49152
	ds_read_b128 v[166:169], v226 offset:50176
	ds_read_b128 v[170:173], v226 offset:51200
	ds_read_b128 v[174:177], v226 offset:52224
	ds_read_b128 v[196:199], v226 offset:53248
	ds_read_b128 v[200:203], v226 offset:54272
	ds_read_b128 v[204:207], v226 offset:55296
	ds_read_b128 v[208:211], v226 offset:56320
	global_load_lds_dwordx4 v[212:213], off
	v_lshl_add_u64 v[212:213], v[214:215], 0, s[94:95]
	s_add_i32 m0, s50, 0x2000
	s_add_i32 s50, s69, s63
	global_load_lds_dwordx4 v[212:213], off
	v_lshl_add_u64 v[212:213], v[216:217], 0, s[94:95]
	s_mov_b32 m0, s50
	s_nop 0
	global_load_lds_dwordx4 v[212:213], off
	v_lshl_add_u64 v[212:213], v[218:219], 0, s[94:95]
	s_add_i32 m0, s50, 0x2000
	s_nop 0
	global_load_lds_dwordx4 v[212:213], off
	v_lshl_add_u64 v[212:213], v[232:233], 0, s[94:95]
	s_mov_b32 m0, s87
	s_nop 0
	global_load_lds_dwordx4 v[212:213], off
	v_lshl_add_u64 v[212:213], v[234:235], 0, s[94:95]
	s_mov_b32 m0, s2
	s_nop 0
	global_load_lds_dwordx4 v[212:213], off
	s_waitcnt vmcnt(8)
	s_waitcnt lgkmcnt(0)
	s_barrier
	s_setprio 1
	s_waitcnt lgkmcnt(0)
	v_mfma_f32_16x16x32_bf16 v[62:65], v[130:133], v[162:165], v[62:65]
	v_mfma_f32_16x16x32_bf16 v[58:61], v[138:141], v[162:165], v[58:61]
	v_mfma_f32_16x16x32_bf16 v[54:57], v[130:133], v[170:173], v[54:57]
	v_mfma_f32_16x16x32_bf16 v[50:53], v[138:141], v[170:173], v[50:53]
	v_mfma_f32_16x16x32_bf16 v[38:41], v[130:133], v[196:199], v[38:41]
	v_mfma_f32_16x16x32_bf16 v[34:37], v[138:141], v[196:199], v[34:37]
	v_mfma_f32_16x16x32_bf16 v[22:25], v[130:133], v[204:207], v[22:25]
	v_mfma_f32_16x16x32_bf16 v[18:21], v[138:141], v[204:207], v[18:21]
	v_mfma_f32_16x16x32_bf16 v[62:65], v[134:137], v[166:169], v[62:65]
	v_mfma_f32_16x16x32_bf16 v[58:61], v[142:145], v[166:169], v[58:61]
	v_mfma_f32_16x16x32_bf16 v[54:57], v[134:137], v[174:177], v[54:57]
	v_mfma_f32_16x16x32_bf16 v[50:53], v[142:145], v[174:177], v[50:53]
	v_mfma_f32_16x16x32_bf16 v[38:41], v[134:137], v[200:203], v[38:41]
	v_mfma_f32_16x16x32_bf16 v[34:37], v[142:145], v[200:203], v[34:37]
	v_mfma_f32_16x16x32_bf16 v[22:25], v[134:137], v[208:211], v[22:25]
	v_mfma_f32_16x16x32_bf16 v[18:21], v[142:145], v[208:211], v[18:21]
	s_setprio 0
	s_setprio 1
	v_mfma_f32_16x16x32_bf16 v[46:49], v[146:149], v[162:165], v[46:49]
	v_mfma_f32_16x16x32_bf16 v[42:45], v[154:157], v[162:165], v[42:45]
	v_mfma_f32_16x16x32_bf16 v[30:33], v[146:149], v[170:173], v[30:33]
	v_mfma_f32_16x16x32_bf16 v[26:29], v[154:157], v[170:173], v[26:29]
	v_mfma_f32_16x16x32_bf16 v[14:17], v[146:149], v[196:199], v[14:17]
	v_mfma_f32_16x16x32_bf16 v[10:13], v[154:157], v[196:199], v[10:13]
	v_mfma_f32_16x16x32_bf16 v[6:9], v[146:149], v[204:207], v[6:9]
	v_mfma_f32_16x16x32_bf16 v[2:5], v[154:157], v[204:207], v[2:5]
	v_mfma_f32_16x16x32_bf16 v[46:49], v[150:153], v[166:169], v[46:49]
	v_mfma_f32_16x16x32_bf16 v[42:45], v[158:161], v[166:169], v[42:45]
	v_mfma_f32_16x16x32_bf16 v[30:33], v[150:153], v[174:177], v[30:33]
	v_mfma_f32_16x16x32_bf16 v[26:29], v[158:161], v[174:177], v[26:29]
	v_mfma_f32_16x16x32_bf16 v[14:17], v[150:153], v[200:203], v[14:17]
	v_mfma_f32_16x16x32_bf16 v[10:13], v[158:161], v[200:203], v[10:13]
	v_mfma_f32_16x16x32_bf16 v[6:9], v[150:153], v[208:211], v[6:9]
	v_mfma_f32_16x16x32_bf16 v[2:5], v[158:161], v[208:211], v[2:5]
	s_setprio 0
	s_barrier
	s_add_u32 s48, s48, 0x100
	s_addc_u32 s49, s49, 0
	s_add_u32 s56, s56, 0x100
	s_addc_u32 s57, s57, 0
	s_cmp_ge_i32 vcc_lo, s55
	s_mov_b32 s50, vcc_lo
	s_cbranch_scc0 .LBB0_344

.LBB0_347:
	s_mov_b32 s100, 0
	s_lshl_b32 s15, s54, 8
	s_add_i32 s15, s15, s86
	v_or_b32_e32 v196, s15, v188
	s_cmp_lt_i32 s58, 2
	s_mov_b64 s[48:49], -1
	s_cbranch_scc1 .LBB0_388
	s_cmp_gt_i32 s58, 2
	s_cbranch_scc0 .LBB0_374
	v_lshl_or_b32 v162, s23, 7, v224
	v_ashrrev_i32_e32 v163, 31, v162
	v_readlane_b32 s48, v244, 30
	v_lshlrev_b64 v[164:165], 2, v[162:163]
	v_readlane_b32 s49, v244, 31
	v_lshl_add_u64 v[134:135], s[92:93], 0, v[164:165]
	v_lshl_add_u64 v[158:159], s[26:27], 0, v[164:165]
	v_lshl_add_u64 v[138:139], s[48:49], 0, v[164:165]
	v_readlane_b32 s48, v244, 32
	v_readlane_b32 s49, v244, 33
	global_load_dwordx4 v[130:133], v[134:135], off offset:16
	global_load_dwordx4 v[146:149], v[134:135], off
	v_lshl_add_u64 v[142:143], s[48:49], 0, v[164:165]
	global_load_dwordx4 v[134:137], v[138:139], off offset:16
	global_load_dwordx4 v[150:153], v[138:139], off
	s_nop 0
	global_load_dwordx4 v[138:141], v[142:143], off offset:16
	global_load_dwordx4 v[154:157], v[142:143], off
	s_nop 0
	global_load_dwordx4 v[142:145], v[158:159], off offset:16
	s_nop 0
	global_load_dwordx4 v[158:161], v[158:159], off
	v_mov_b32_e32 v199, v1
	v_mov_b32_e32 v201, v1
	s_nop 0
	v_mov_b32_dpp v199, v199 row_ror:1 row_mask:0xf bank_mask:0xf
	v_mov_b32_dpp v201, v201 row_ror:2 row_mask:0xf bank_mask:0xf
	v_mov_b32_e32 v166, v199
	v_mov_b32_e32 v168, v201
	v_mov_b32_e32 v167, v199
	v_mov_b32_e32 v169, v201
	v_mov_b32_e32 v170, v199
	v_mov_b32_e32 v172, v201
	v_mov_b32_e32 v171, v199
	v_mov_b32_e32 v173, v201
	v_mov_b32_e32 v174, v199
	v_mov_b32_e32 v176, v201
	v_mov_b32_e32 v175, v199
	v_mov_b32_e32 v177, v201
	v_mov_b32_e32 v198, v199
	v_mov_b32_e32 v200, v201
	v_mov_b32_dpp v166, v126 row_shr:1 row_mask:0xf bank_mask:0xf
	v_mov_b32_dpp v168, v126 row_shr:2 row_mask:0xf bank_mask:0xf
	v_mov_b32_dpp v167, v127 row_shr:1 row_mask:0xf bank_mask:0xf
	v_mov_b32_dpp v169, v127 row_shr:2 row_mask:0xf bank_mask:0xf
	v_mov_b32_dpp v170, v128 row_shr:1 row_mask:0xf bank_mask:0xf
	v_mov_b32_dpp v172, v128 row_shr:2 row_mask:0xf bank_mask:0xf
	v_mov_b32_dpp v171, v129 row_shr:1 row_mask:0xf bank_mask:0xf
	v_mov_b32_dpp v173, v129 row_shr:2 row_mask:0xf bank_mask:0xf
	v_mov_b32_dpp v174, v122 row_shr:1 row_mask:0xf bank_mask:0xf
	v_mov_b32_dpp v176, v122 row_shr:2 row_mask:0xf bank_mask:0xf
	v_mov_b32_dpp v175, v123 row_shr:1 row_mask:0xf bank_mask:0xf
	v_mov_b32_dpp v177, v123 row_shr:2 row_mask:0xf bank_mask:0xf
	v_mov_b32_dpp v198, v124 row_shr:1 row_mask:0xf bank_mask:0xf
	v_mov_b32_dpp v200, v124 row_shr:2 row_mask:0xf bank_mask:0xf
	v_mov_b32_dpp v199, v125 row_shr:1 row_mask:0xf bank_mask:0xf
	v_mov_b32_dpp v201, v125 row_shr:2 row_mask:0xf bank_mask:0xf
	s_and_saveexec_b64 s[48:49], s[42:43]
	s_xor_b64 s[48:49], exec, s[48:49]
	s_movk_i32 s70, 0x5800
	s_cbranch_execz .LBB0_351
	s_waitcnt vmcnt(0)
	s_mov_b32 s100, 1
	v_pk_fma_f32 v[200:201], v[132:133], v[200:201], v[144:145]
	v_pk_fma_f32 v[176:177], v[130:131], v[176:177], v[142:143]
	v_pk_fma_f32 v[198:199], v[136:137], v[198:199], v[200:201]
	v_pk_fma_f32 v[174:175], v[134:135], v[174:175], v[176:177]
	v_pk_fma_f32 v[198:199], v[124:125], v[140:141], v[198:199]
	v_pk_fma_f32 v[174:175], v[122:123], v[138:139], v[174:175]
	v_mul_f32_e32 v0, 0xbfb8aa3b, v198
	v_exp_f32_e32 v0, v0
	v_mul_f32_e32 v197, 0xbfb8aa3b, v199
	v_exp_f32_e32 v197, v197
	v_pk_fma_f32 v[172:173], v[148:149], v[172:173], v[160:161]
	v_add_f32_e32 v0, 1.0, v0
	v_rcp_f32_e32 v200, v0
	v_add_f32_e32 v197, 1.0, v197
	v_mul_f32_e32 v0, 0xbfb8aa3b, v174
	v_rcp_f32_e32 v201, v197
	v_exp_f32_e32 v0, v0
	v_mul_f32_e32 v197, 0xbfb8aa3b, v175
	v_exp_f32_e32 v197, v197
	v_pk_fma_f32 v[170:171], v[152:153], v[170:171], v[172:173]
	v_add_f32_e32 v0, 1.0, v0
	v_pk_mul_f32 v[176:177], v[198:199], v[200:201]
	v_rcp_f32_e32 v198, v0
	v_add_f32_e32 v0, 1.0, v197
	v_pk_fma_f32 v[170:171], v[128:129], v[156:157], v[170:171]
	v_pk_fma_f32 v[168:169], v[146:147], v[168:169], v[158:159]
	v_rcp_f32_e32 v199, v0
	v_mul_f32_e32 v0, 0xbfb8aa3b, v170
	v_pk_fma_f32 v[166:167], v[150:151], v[166:167], v[168:169]
	v_exp_f32_e32 v0, v0
	v_mul_f32_e32 v172, 0xbfb8aa3b, v171
	v_pk_fma_f32 v[166:167], v[126:127], v[154:155], v[166:167]
	v_exp_f32_e32 v197, v172
	v_mul_f32_e32 v168, 0xbfb8aa3b, v166
	v_exp_f32_e32 v168, v168
	v_mul_f32_e32 v169, 0xbfb8aa3b, v167
	v_exp_f32_e32 v169, v169
	v_add_f32_e32 v0, 1.0, v0
	v_pk_mul_f32 v[172:173], v[174:175], v[198:199]
	v_rcp_f32_e32 v174, v0
	v_add_f32_e32 v0, 1.0, v197
	v_rcp_f32_e32 v175, v0
	v_add_f32_e32 v0, 1.0, v168
	v_rcp_f32_e32 v168, v0
	v_add_f32_e32 v0, 1.0, v169
	v_rcp_f32_e32 v169, v0
	v_pk_mul_f32 v[170:171], v[170:171], v[174:175]
	s_movk_i32 s50, 0x2c00
	v_pk_mul_f32 v[170:171], v[112:113], v[170:171]
	v_pk_mul_f32 v[166:167], v[166:167], v[168:169]
	v_pk_mul_f32 v[176:177], v[108:109], v[176:177]
	v_pk_mul_f32 v[166:167], v[110:111], v[166:167]
	v_pk_mul_f32 v[172:173], v[106:107], v[172:173]
	v_cvt_pk_bf16_f32 v166, v166, v167
	v_cvt_pk_bf16_f32 v167, v170, v171
	v_mov_b64_e32 v[170:171], s[24:25]
	v_mad_i64_i32 v[170:171], s[50:51], v196, s50, v[170:171]
	v_cvt_pk_bf16_f32 v168, v172, v173
	v_cvt_pk_bf16_f32 v169, v176, v177
	v_lshl_add_u64 v[170:171], v[162:163], 1, v[170:171]
	global_store_dwordx4 v[170:171], v[166:169], off

.LBB0_353:
	s_or_b64 exec, exec, s[48:49]
	v_mov_b32_e32 v172, v1
	v_mov_b32_e32 v173, v1
	v_mov_b32_e32 v170, v1
	v_mov_b32_dpp v172, v126 row_ror:2 row_mask:0xf bank_mask:0xf
	v_mov_b32_e32 v171, v1
	v_mov_b32_dpp v173, v127 row_ror:2 row_mask:0xf bank_mask:0xf
	v_mov_b32_dpp v170, v126 row_ror:1 row_mask:0xf bank_mask:0xf
	v_mov_b32_dpp v172, v118 row_shr:2 row_mask:0xf bank_mask:0xf
	v_mov_b32_dpp v171, v127 row_ror:1 row_mask:0xf bank_mask:0xf
	v_mov_b32_dpp v173, v119 row_shr:2 row_mask:0xf bank_mask:0xf
	v_mov_b32_dpp v170, v118 row_shr:1 row_mask:0xf bank_mask:0xf
	v_mov_b32_dpp v171, v119 row_shr:1 row_mask:0xf bank_mask:0xf
	s_waitcnt vmcnt(0)
	s_mov_b32 s100, 1
	v_pk_fma_f32 v[172:173], v[146:147], v[172:173], v[158:159]
	v_mov_b32_e32 v174, v1
	v_pk_fma_f32 v[170:171], v[150:151], v[170:171], v[172:173]
	v_mov_b32_e32 v175, v1
	v_pk_fma_f32 v[170:171], v[118:119], v[154:155], v[170:171]
	v_mov_b32_dpp v174, v128 row_ror:2 row_mask:0xf bank_mask:0xf
	v_mul_f32_e32 v172, 0xbfb8aa3b, v170
	v_mul_f32_e32 v173, 0xbfb8aa3b, v171
	v_exp_f32_e32 v172, v172
	v_exp_f32_e32 v173, v173
	v_mov_b32_dpp v175, v129 row_ror:2 row_mask:0xf bank_mask:0xf
	v_mov_b32_dpp v174, v120 row_shr:2 row_mask:0xf bank_mask:0xf
	v_add_f32_e32 v172, 1.0, v172
	v_add_f32_e32 v173, 1.0, v173
	v_rcp_f32_e32 v172, v172
	v_rcp_f32_e32 v173, v173
	v_mov_b32_dpp v175, v121 row_shr:2 row_mask:0xf bank_mask:0xf
	v_pk_fma_f32 v[174:175], v[148:149], v[174:175], v[160:161]
	v_mov_b32_e32 v176, v1
	v_pk_mul_f32 v[170:171], v[170:171], v[172:173]
	v_mov_b32_e32 v172, v1
	v_mov_b32_e32 v173, v1
	v_mov_b32_e32 v177, v1
	v_mov_b32_dpp v172, v128 row_ror:1 row_mask:0xf bank_mask:0xf
	v_mov_b32_dpp v173, v129 row_ror:1 row_mask:0xf bank_mask:0xf
	v_mov_b32_dpp v176, v122 row_ror:2 row_mask:0xf bank_mask:0xf
	v_mov_b32_dpp v172, v120 row_shr:1 row_mask:0xf bank_mask:0xf
	v_mov_b32_dpp v173, v121 row_shr:1 row_mask:0xf bank_mask:0xf
	v_pk_fma_f32 v[172:173], v[152:153], v[172:173], v[174:175]
	v_mov_b32_dpp v177, v123 row_ror:2 row_mask:0xf bank_mask:0xf
	v_pk_fma_f32 v[172:173], v[120:121], v[156:157], v[172:173]
	v_mov_b32_dpp v176, v114 row_shr:2 row_mask:0xf bank_mask:0xf
	v_mul_f32_e32 v174, 0xbfb8aa3b, v172
	v_mul_f32_e32 v175, 0xbfb8aa3b, v173
	v_exp_f32_e32 v174, v174
	v_exp_f32_e32 v175, v175
	v_mov_b32_dpp v177, v115 row_shr:2 row_mask:0xf bank_mask:0xf
	v_pk_fma_f32 v[176:177], v[130:131], v[176:177], v[142:143]
	v_add_f32_e32 v174, 1.0, v174
	v_add_f32_e32 v175, 1.0, v175
	v_rcp_f32_e32 v174, v174
	v_rcp_f32_e32 v175, v175
	v_mov_b32_e32 v198, v1
	v_mov_b32_e32 v199, v1
	v_pk_mul_f32 v[170:171], v[94:95], v[170:171]
	v_pk_mul_f32 v[172:173], v[172:173], v[174:175]
	v_mov_b32_e32 v174, v1
	v_mov_b32_e32 v175, v1
	v_mov_b32_dpp v198, v124 row_ror:2 row_mask:0xf bank_mask:0xf
	v_mov_b32_dpp v174, v122 row_ror:1 row_mask:0xf bank_mask:0xf
	v_mov_b32_dpp v175, v123 row_ror:1 row_mask:0xf bank_mask:0xf
	v_mov_b32_dpp v199, v125 row_ror:2 row_mask:0xf bank_mask:0xf
	v_mov_b32_dpp v174, v114 row_shr:1 row_mask:0xf bank_mask:0xf
	v_mov_b32_dpp v175, v115 row_shr:1 row_mask:0xf bank_mask:0xf
	v_pk_fma_f32 v[174:175], v[134:135], v[174:175], v[176:177]
	v_mov_b32_dpp v198, v116 row_shr:2 row_mask:0xf bank_mask:0xf
	v_pk_fma_f32 v[174:175], v[114:115], v[138:139], v[174:175]
	v_mov_b32_dpp v199, v117 row_shr:2 row_mask:0xf bank_mask:0xf
	v_mul_f32_e32 v176, 0xbfb8aa3b, v174
	v_mul_f32_e32 v177, 0xbfb8aa3b, v175
	v_exp_f32_e32 v176, v176
	v_exp_f32_e32 v177, v177
	v_pk_fma_f32 v[198:199], v[132:133], v[198:199], v[144:145]
	v_pk_mul_f32 v[172:173], v[96:97], v[172:173]
	v_add_f32_e32 v176, 1.0, v176
	v_add_f32_e32 v177, 1.0, v177
	v_rcp_f32_e32 v176, v176
	v_rcp_f32_e32 v177, v177
	s_cmp_gt_i32 s54, 31
	v_or_b32_e32 v0, 16, v196
	v_cvt_pk_bf16_f32 v170, v170, v171
	v_pk_mul_f32 v[174:175], v[174:175], v[176:177]
	v_mov_b32_e32 v176, v1
	v_mov_b32_e32 v177, v1
	v_pk_mul_f32 v[174:175], v[90:91], v[174:175]
	v_mov_b32_dpp v176, v124 row_ror:1 row_mask:0xf bank_mask:0xf
	v_mov_b32_dpp v177, v125 row_ror:1 row_mask:0xf bank_mask:0xf
	v_cvt_pk_bf16_f32 v171, v172, v173
	v_mov_b32_dpp v176, v116 row_shr:1 row_mask:0xf bank_mask:0xf
	v_mov_b32_dpp v177, v117 row_shr:1 row_mask:0xf bank_mask:0xf
	v_pk_fma_f32 v[176:177], v[136:137], v[176:177], v[198:199]
	v_cvt_pk_bf16_f32 v172, v174, v175
	v_pk_fma_f32 v[176:177], v[116:117], v[140:141], v[176:177]
	v_mov_b64_e32 v[174:175], s[24:25]
	v_mul_f32_e32 v197, 0xbfb8aa3b, v176
	v_exp_f32_e32 v197, v197
	s_movk_i32 s54, 0x2c00
	s_cselect_b64 s[48:49], -1, 0
	v_mad_i64_i32 v[174:175], s[54:55], v0, s54, v[174:175]
	v_add_f32_e32 v197, 1.0, v197
	v_rcp_f32_e32 v198, v197
	v_mul_f32_e32 v197, 0xbfb8aa3b, v177
	v_exp_f32_e32 v197, v197
	v_lshl_add_u64 v[164:165], v[162:163], 2, s[74:75]
	s_and_b64 s[50:51], s[44:45], s[48:49]
	v_lshl_add_u64 v[174:175], v[162:163], 1, v[174:175]
	v_add_f32_e32 v197, 1.0, v197
	v_rcp_f32_e32 v199, v197
	s_nop 0
	v_pk_mul_f32 v[176:177], v[176:177], v[198:199]
	s_nop 0
	v_pk_mul_f32 v[176:177], v[92:93], v[176:177]
	s_nop 0
	v_cvt_pk_bf16_f32 v173, v176, v177
	global_store_dwordx4 v[174:175], v[170:173], off
	s_and_saveexec_b64 s[54:55], s[50:51]
	s_cbranch_execz .LBB0_355
	s_ashr_i32 s15, s15, 4
	v_add_u32_e32 v0, s15, v190
	v_mad_i64_i32 v[170:171], s[56:57], v0, s70, v[164:165]
	global_store_dwordx4 v[170:171], v[118:121], off
	global_store_dwordx4 v[170:171], v[114:117], off offset:16

.LBB0_374:
	s_and_b64 vcc, exec, s[48:49]
	s_cbranch_vccz .LBB0_387
	v_lshl_or_b32 v202, s23, 8, v225
	s_cmp_lt_i32 s88, 0
	s_mov_b64 s[48:49], -1
	v_ashrrev_i32_e32 v203, 31, v202
	v_add_u32_e32 v204, 0xffffe000, v196
	v_add_u32_e32 v200, 0xffffe010, v196
	v_add_u32_e32 v198, 0xffffe020, v196
	s_cbranch_scc0 .LBB0_385
	s_cmp_lt_i32 s55, 32
	s_cbranch_scc0 .Lrk_store
	s_movk_i32 s15, 0x2000
	v_ashrrev_i32_e32 v197, 31, v196
	v_cmp_gt_i32_e32 vcc, s15, v196
	v_mov_b32_e32 v0, s77
	v_mov_b32_e32 v134, s19
	v_cndmask_b32_e32 v131, 0, v197, vcc
	v_cndmask_b32_e32 v130, v204, v196, vcc
	v_mov_b32_e32 v135, s76
	v_mov_b32_e32 v136, s18
	v_cndmask_b32_e32 v133, v0, v134, vcc
	v_cndmask_b32_e32 v132, v135, v136, vcc
	v_lshlrev_b64 v[130:131], 13, v[130:131]
	v_lshl_add_u64 v[130:131], v[132:133], 0, v[130:131]
	v_lshlrev_b64 v[206:207], 2, v[202:203]
	v_or_b32_e32 v212, 16, v196
	v_lshl_add_u64 v[130:131], v[130:131], 0, v[206:207]
	v_ashrrev_i32_e32 v213, 31, v212
	v_cmp_gt_i32_e32 vcc, s15, v212
	global_load_dwordx4 v[174:177], v[130:131], off
	global_load_dwordx4 v[170:173], v[130:131], off offset:64
	global_load_dwordx4 v[166:169], v[130:131], off offset:512
	global_load_dwordx4 v[162:165], v[130:131], off offset:576
	v_cndmask_b32_e32 v131, 0, v213, vcc
	v_cndmask_b32_e32 v130, v200, v212, vcc
	v_cndmask_b32_e32 v133, v0, v134, vcc
	v_cndmask_b32_e32 v132, v135, v136, vcc
	v_lshlrev_b64 v[130:131], 13, v[130:131]
	v_lshl_add_u64 v[130:131], v[132:133], 0, v[130:131]
	v_or_b32_e32 v210, 32, v196
	v_lshl_add_u64 v[130:131], v[130:131], 0, v[206:207]
	v_ashrrev_i32_e32 v211, 31, v210
	v_cmp_gt_i32_e32 vcc, s15, v210
	global_load_dwordx4 v[158:161], v[130:131], off
	global_load_dwordx4 v[154:157], v[130:131], off offset:64
	global_load_dwordx4 v[150:153], v[130:131], off offset:512
	global_load_dwordx4 v[146:149], v[130:131], off offset:576
	v_cndmask_b32_e32 v131, 0, v211, vcc
	v_cndmask_b32_e32 v130, v198, v210, vcc
	v_cndmask_b32_e32 v133, v0, v134, vcc
	v_cndmask_b32_e32 v132, v135, v136, vcc
	v_lshlrev_b64 v[130:131], 13, v[130:131]
	v_lshl_add_u64 v[130:131], v[132:133], 0, v[130:131]
	v_lshl_add_u64 v[130:131], v[130:131], 0, v[206:207]
	global_load_dwordx4 v[142:145], v[130:131], off
	global_load_dwordx4 v[138:141], v[130:131], off offset:64
	global_load_dwordx4 v[134:137], v[130:131], off offset:512
	s_nop 0
	global_load_dwordx4 v[130:133], v[130:131], off offset:576
	v_or_b32_e32 v214, 48, v196
	s_movk_i32 s15, 0x1fff
	v_cmp_lt_i32_e32 vcc, s15, v214
	s_and_saveexec_b64 s[48:49], vcc
	s_xor_b64 s[48:49], exec, s[48:49]
	v_add_u32_e32 v0, 0xffffe030, v196
	v_lshlrev_b64 v[208:209], 13, v[0:1]
	v_mov_b32_e32 v215, v1
	v_lshl_add_u64 v[216:217], s[76:77], 0, v[208:209]
	v_lshlrev_b64 v[208:209], 13, v[214:215]
	s_andn2_saveexec_b64 s[48:49], s[48:49]
	v_ashrrev_i32_e32 v215, 31, v214
	v_lshlrev_b64 v[208:209], 13, v[214:215]
	v_lshl_add_u64 v[216:217], s[18:19], 0, v[208:209]
	s_or_b64 exec, exec, s[48:49]
	v_lshl_add_u64 v[218:219], v[216:217], 0, v[206:207]
	global_load_dwordx4 v[214:217], v[218:219], off
	global_load_dwordx4 v[232:235], v[218:219], off offset:64
	global_load_dwordx4 v[236:239], v[218:219], off offset:512
	global_load_dwordx4 v[240:243], v[218:219], off offset:576
	v_lshlrev_b64 v[218:219], 13, v[196:197]
	v_lshl_add_u64 v[218:219], s[78:79], 0, v[218:219]
	v_lshl_add_u64 v[218:219], v[218:219], 0, v[206:207]
	s_waitcnt vmcnt(0)
	s_mov_b32 s100, 1
	v_pk_add_f32 v[164:165], v[108:109], v[164:165]
	v_pk_add_f32 v[162:163], v[106:107], v[162:163]
	global_store_dwordx4 v[218:219], v[162:165], off offset:576
	v_pk_add_f32 v[148:149], v[92:93], v[148:149]
	v_pk_add_f32 v[146:147], v[90:91], v[146:147]
	v_lshlrev_b64 v[162:163], 13, v[212:213]
	v_lshl_add_u64 v[162:163], s[78:79], 0, v[162:163]
	v_lshl_add_u64 v[162:163], v[162:163], 0, v[206:207]
	global_store_dwordx4 v[162:163], v[146:149], off offset:576
	v_pk_add_f32 v[132:133], v[76:77], v[132:133]
	v_pk_add_f32 v[130:131], v[74:75], v[130:131]
	v_lshlrev_b64 v[146:147], 13, v[210:211]
	v_lshl_add_u64 v[146:147], s[78:79], 0, v[146:147]
	v_lshl_add_u64 v[146:147], v[146:147], 0, v[206:207]
	v_pk_add_f32 v[136:137], v[80:81], v[136:137]
	v_pk_add_f32 v[134:135], v[78:79], v[134:135]
	global_store_dwordx4 v[146:147], v[130:133], off offset:576
	v_pk_add_f32 v[176:177], v[176:177], v[128:129]
	v_pk_add_f32 v[174:175], v[174:175], v[126:127]
	v_lshl_add_u64 v[130:131], s[78:79], 0, v[208:209]
	v_pk_add_f32 v[172:173], v[172:173], v[124:125]
	v_pk_add_f32 v[170:171], v[170:171], v[122:123]
	v_pk_add_f32 v[168:169], v[112:113], v[168:169]
	v_pk_add_f32 v[166:167], v[110:111], v[166:167]
	v_pk_add_f32 v[160:161], v[160:161], v[120:121]
	v_pk_add_f32 v[158:159], v[158:159], v[118:119]
	v_pk_add_f32 v[156:157], v[156:157], v[116:117]
	v_pk_add_f32 v[154:155], v[154:155], v[114:115]
	v_pk_add_f32 v[152:153], v[96:97], v[152:153]
	v_pk_add_f32 v[150:151], v[94:95], v[150:151]
	v_pk_add_f32 v[144:145], v[144:145], v[104:105]
	v_pk_add_f32 v[142:143], v[142:143], v[102:103]
	v_pk_add_f32 v[140:141], v[140:141], v[100:101]
	v_pk_add_f32 v[138:139], v[138:139], v[98:99]
	global_store_dwordx4 v[146:147], v[134:137], off offset:512
	global_store_dwordx4 v[218:219], v[174:177], off
	global_store_dwordx4 v[218:219], v[170:173], off offset:64
	v_lshl_add_u64 v[134:135], v[130:131], 0, v[206:207]
	global_store_dwordx4 v[218:219], v[166:169], off offset:512
	global_store_dwordx4 v[162:163], v[158:161], off
	global_store_dwordx4 v[162:163], v[154:157], off offset:64
	global_store_dwordx4 v[162:163], v[150:153], off offset:512
	global_store_dwordx4 v[146:147], v[142:145], off
	global_store_dwordx4 v[146:147], v[138:141], off offset:64
	s_movk_i32 s15, 0x1f80
	v_add_u32_e32 v208, 0x80, v196
	v_cmp_gt_i32_e32 vcc, s15, v196
	v_add_u32_e32 v0, 0xffffe080, v196
	v_ashrrev_i32_e32 v209, 31, v208
	v_mov_b32_e32 v150, s19
	v_mov_b32_e32 v151, s76
	v_mov_b32_e32 v152, s18
	v_add_u32_e32 v210, 0x90, v196
	s_movk_i32 s15, 0x1f70
	v_ashrrev_i32_e32 v211, 31, v210
	v_add_u32_e32 v146, 0xffffe090, v196
	v_pk_add_f32 v[132:133], v[88:89], v[216:217]
	v_pk_add_f32 v[130:131], v[86:87], v[214:215]
	global_store_dwordx4 v[134:135], v[130:133], off
	v_add_u32_e32 v214, 0xa0, v196
	v_ashrrev_i32_e32 v215, 31, v214
	v_pk_add_f32 v[132:133], v[84:85], v[234:235]
	v_pk_add_f32 v[130:131], v[82:83], v[232:233]
	global_store_dwordx4 v[134:135], v[130:133], off offset:64
	v_add_u32_e32 v216, 0xb0, v196
	s_nop 0
	v_pk_add_f32 v[132:133], v[72:73], v[238:239]
	v_pk_add_f32 v[130:131], v[70:71], v[236:237]
	global_store_dwordx4 v[134:135], v[130:133], off offset:512
	s_nop 1
	v_pk_add_f32 v[132:133], v[68:69], v[242:243]
	v_pk_add_f32 v[130:131], v[66:67], v[240:241]
	global_store_dwordx4 v[134:135], v[130:133], off offset:576
	s_nop 1
	v_cndmask_b32_e32 v130, v0, v208, vcc
	v_mov_b32_e32 v0, s77
	v_cndmask_b32_e32 v131, 0, v209, vcc
	v_cndmask_b32_e32 v133, v0, v150, vcc
	v_cndmask_b32_e32 v132, v151, v152, vcc
	v_cmp_gt_i32_e32 vcc, s15, v196
	v_lshlrev_b64 v[130:131], 13, v[130:131]
	v_lshl_add_u64 v[130:131], v[132:133], 0, v[130:131]
	v_cndmask_b32_e32 v147, 0, v211, vcc
	v_cndmask_b32_e32 v146, v146, v210, vcc
	v_cndmask_b32_e32 v149, v0, v150, vcc
	v_cndmask_b32_e32 v148, v151, v152, vcc
	v_lshlrev_b64 v[146:147], 13, v[146:147]
	v_lshl_add_u64 v[146:147], v[148:149], 0, v[146:147]
	v_lshl_add_u64 v[130:131], v[130:131], 0, v[206:207]
	v_lshl_add_u64 v[146:147], v[146:147], 0, v[206:207]
	s_movk_i32 s15, 0x1f60
	global_load_dwordx4 v[142:145], v[130:131], off
	global_load_dwordx4 v[138:141], v[130:131], off offset:64
	global_load_dwordx4 v[134:137], v[130:131], off offset:512
	s_nop 0
	global_load_dwordx4 v[130:133], v[130:131], off offset:576
	s_nop 0
	global_load_dwordx4 v[174:177], v[146:147], off
	global_load_dwordx4 v[170:173], v[146:147], off offset:64
	global_load_dwordx4 v[162:165], v[146:147], off offset:512
	global_load_dwordx4 v[154:157], v[146:147], off offset:576
	v_cmp_gt_i32_e32 vcc, s15, v196
	v_add_u32_e32 v146, 0xffffe0a0, v196
	s_movk_i32 s15, 0x1f4f
	v_cndmask_b32_e32 v147, 0, v215, vcc
	v_cndmask_b32_e32 v146, v146, v214, vcc
	v_cndmask_b32_e32 v149, v0, v150, vcc
	v_cndmask_b32_e32 v148, v151, v152, vcc
	v_lshlrev_b64 v[146:147], 13, v[146:147]
	v_lshl_add_u64 v[146:147], v[148:149], 0, v[146:147]
	v_lshl_add_u64 v[146:147], v[146:147], 0, v[206:207]
	global_load_dwordx4 v[166:169], v[146:147], off
	global_load_dwordx4 v[158:161], v[146:147], off offset:64
	global_load_dwordx4 v[150:153], v[146:147], off offset:512
	s_nop 0
	global_load_dwordx4 v[146:149], v[146:147], off offset:576
	v_cmp_lt_i32_e32 vcc, s15, v196
	s_and_saveexec_b64 s[48:49], vcc
	s_xor_b64 s[48:49], exec, s[48:49]
	v_add_u32_e32 v0, 0xffffe0b0, v196
	v_lshlrev_b64 v[212:213], 13, v[0:1]
	v_mov_b32_e32 v217, v1
	v_lshl_add_u64 v[218:219], s[76:77], 0, v[212:213]
	v_lshlrev_b64 v[212:213], 13, v[216:217]
	s_andn2_saveexec_b64 s[48:49], s[48:49]
	v_ashrrev_i32_e32 v217, 31, v216
	v_lshlrev_b64 v[212:213], 13, v[216:217]
	v_lshl_add_u64 v[218:219], s[18:19], 0, v[212:213]
	s_or_b64 exec, exec, s[48:49]
	v_lshl_add_u64 v[240:241], v[218:219], 0, v[206:207]
	global_load_dwordx4 v[216:219], v[240:241], off
	global_load_dwordx4 v[232:235], v[240:241], off offset:64
	global_load_dwordx4 v[236:239], v[240:241], off offset:512
	s_nop 0
	global_load_dwordx4 v[240:243], v[240:241], off offset:576
	v_lshlrev_b64 v[208:209], 13, v[208:209]
	v_lshlrev_b64 v[210:211], 13, v[210:211]
	v_lshlrev_b64 v[214:215], 13, v[214:215]
	v_lshl_add_u64 v[208:209], s[78:79], 0, v[208:209]
	s_waitcnt vmcnt(15)
	v_pk_add_f32 v[144:145], v[144:145], v[64:65]
	v_pk_add_f32 v[142:143], v[142:143], v[62:63]
	s_waitcnt vmcnt(12)
	v_pk_add_f32 v[132:133], v[44:45], v[132:133]
	v_pk_add_f32 v[130:131], v[42:43], v[130:131]
	v_lshl_add_u64 v[212:213], s[78:79], 0, v[212:213]
	v_lshl_add_u64 v[210:211], s[78:79], 0, v[210:211]
	v_lshl_add_u64 v[214:215], s[78:79], 0, v[214:215]
	v_lshl_add_u64 v[208:209], v[208:209], 0, v[206:207]
	v_pk_add_f32 v[140:141], v[140:141], v[60:61]
	v_pk_add_f32 v[138:139], v[138:139], v[58:59]
	v_pk_add_f32 v[136:137], v[48:49], v[136:137]
	v_pk_add_f32 v[134:135], v[46:47], v[134:135]
	s_waitcnt vmcnt(11)
	v_pk_add_f32 v[176:177], v[176:177], v[56:57]
	v_pk_add_f32 v[174:175], v[174:175], v[54:55]
	s_waitcnt vmcnt(10)
	v_pk_add_f32 v[172:173], v[172:173], v[52:53]
	v_pk_add_f32 v[170:171], v[170:171], v[50:51]
	s_waitcnt vmcnt(9)
	v_pk_add_f32 v[164:165], v[32:33], v[164:165]
	v_pk_add_f32 v[162:163], v[30:31], v[162:163]
	s_waitcnt vmcnt(8)
	v_pk_add_f32 v[156:157], v[28:29], v[156:157]
	v_pk_add_f32 v[154:155], v[26:27], v[154:155]
	s_waitcnt vmcnt(7)
	v_pk_add_f32 v[168:169], v[168:169], v[40:41]
	v_pk_add_f32 v[166:167], v[166:167], v[38:39]
	s_waitcnt vmcnt(6)
	v_pk_add_f32 v[160:161], v[160:161], v[36:37]
	v_pk_add_f32 v[158:159], v[158:159], v[34:35]
	s_waitcnt vmcnt(5)
	v_pk_add_f32 v[152:153], v[16:17], v[152:153]
	v_pk_add_f32 v[150:151], v[14:15], v[150:151]
	s_waitcnt vmcnt(4)
	v_pk_add_f32 v[148:149], v[12:13], v[148:149]
	v_pk_add_f32 v[146:147], v[10:11], v[146:147]
	v_lshl_add_u64 v[212:213], v[212:213], 0, v[206:207]
	v_lshl_add_u64 v[210:211], v[210:211], 0, v[206:207]
	v_lshl_add_u64 v[206:207], v[214:215], 0, v[206:207]
	global_store_dwordx4 v[208:209], v[142:145], off
	global_store_dwordx4 v[208:209], v[138:141], off offset:64
	global_store_dwordx4 v[208:209], v[134:137], off offset:512
	global_store_dwordx4 v[208:209], v[130:133], off offset:576
	global_store_dwordx4 v[210:211], v[174:177], off
	global_store_dwordx4 v[210:211], v[170:173], off offset:64
	global_store_dwordx4 v[210:211], v[162:165], off offset:512
	global_store_dwordx4 v[210:211], v[154:157], off offset:576
	global_store_dwordx4 v[206:207], v[166:169], off
	global_store_dwordx4 v[206:207], v[158:161], off offset:64
	global_store_dwordx4 v[206:207], v[150:153], off offset:512
	global_store_dwordx4 v[206:207], v[146:149], off offset:576
	s_mov_b64 s[48:49], 0
	s_waitcnt vmcnt(15)
	v_pk_add_f32 v[132:133], v[24:25], v[218:219]
	v_pk_add_f32 v[130:131], v[22:23], v[216:217]
	s_waitcnt vmcnt(14)
	v_pk_add_f32 v[136:137], v[20:21], v[234:235]
	v_pk_add_f32 v[134:135], v[18:19], v[232:233]
	s_waitcnt vmcnt(13)
	v_pk_add_f32 v[140:141], v[8:9], v[238:239]
	v_pk_add_f32 v[138:139], v[6:7], v[236:237]
	s_waitcnt vmcnt(12)
	v_pk_add_f32 v[144:145], v[4:5], v[242:243]
	v_pk_add_f32 v[142:143], v[2:3], v[240:241]
	global_store_dwordx4 v[212:213], v[130:133], off
	global_store_dwordx4 v[212:213], v[134:137], off offset:64
	global_store_dwordx4 v[212:213], v[138:141], off offset:512
	global_store_dwordx4 v[212:213], v[142:145], off offset:576

.LBB0_396:
	s_and_b64 vcc, exec, s[50:51]
	s_waitcnt vmcnt(0)
	s_mov_b32 s100, 1
	v_sub_f32_e32 v171, 1.0, v134
	v_sub_f32_e32 v170, 1.0, v130
	v_sub_f32_e32 v169, 1.0, v135
	v_sub_f32_e32 v168, 1.0, v131
	v_sub_f32_e32 v167, 1.0, v136
	v_sub_f32_e32 v166, 1.0, v132
	v_sub_f32_e32 v165, 1.0, v137
	v_sub_f32_e32 v164, 1.0, v133
	s_cbranch_vccz .LBB0_398
	v_mul_f32_e32 v139, 0xbfb8aa3b, v122
	v_mul_f32_e32 v140, 0xbfb8aa3b, v127
	v_exp_f32_e32 v139, v139
	v_exp_f32_e32 v140, v140
	v_mul_f32_e32 v141, 0xbfb8aa3b, v128
	v_exp_f32_e32 v141, v141
	v_add_f32_e32 v139, 1.0, v139
	v_rcp_f32_e32 v139, v139
	v_add_f32_e32 v140, 1.0, v140
	v_rcp_f32_e32 v140, v140
	v_add_f32_e32 v141, 1.0, v141
	v_fma_f32 v139, v139, v170, v130
	v_log_f32_e32 v142, v139
	v_fma_f32 v139, v140, v169, v135
	v_mul_f32_e32 v140, 0xbfb8aa3b, v123
	v_exp_f32_e32 v140, v140
	v_mul_f32_e32 v143, 0xbfb8aa3b, v124
	v_rcp_f32_e32 v141, v141
	v_exp_f32_e32 v143, v143
	v_add_f32_e32 v140, 1.0, v140
	v_rcp_f32_e32 v140, v140
	v_mul_f32_e32 v138, 0xbfb8aa3b, v126
	v_exp_f32_e32 v138, v138
	v_mul_f32_e32 v144, 0xbfb8aa3b, v125
	v_fma_f32 v150, v140, v168, v131
	v_fma_f32 v140, v141, v167, v136
	v_add_f32_e32 v141, 1.0, v143
	v_mul_f32_e32 v143, 0xbfb8aa3b, v129
	v_exp_f32_e32 v143, v143
	v_exp_f32_e32 v144, v144
	v_add_f32_e32 v138, 1.0, v138
	v_rcp_f32_e32 v141, v141
	v_add_f32_e32 v143, 1.0, v143
	v_rcp_f32_e32 v138, v138
	v_rcp_f32_e32 v143, v143
	v_add_f32_e32 v144, 1.0, v144
	v_rcp_f32_e32 v145, v144
	v_fma_f32 v141, v141, v166, v132
	v_fma_f32 v138, v138, v171, v134
	v_log_f32_e32 v144, v141
	v_fma_f32 v141, v143, v165, v137
	v_log_f32_e32 v138, v138
	v_log_f32_e32 v139, v139
	v_log_f32_e32 v140, v140
	v_log_f32_e32 v141, v141
	v_fma_f32 v143, v145, v164, v133
	v_log_f32_e32 v145, v143
	v_log_f32_e32 v143, v150
	v_pk_mul_f32 v[140:141], v[140:141], s[96:97] op_sel_hi:[1,0]
	v_pk_mul_f32 v[138:139], v[138:139], s[96:97] op_sel_hi:[1,0]
	v_lshl_add_u64 v[146:147], v[146:147], 2, s[28:29]
	v_pk_mul_f32 v[144:145], v[144:145], s[96:97] op_sel_hi:[1,0]
	v_pk_mul_f32 v[142:143], v[142:143], s[96:97] op_sel_hi:[1,0]
	global_store_dwordx4 v[146:147], v[138:141], off
	global_store_dwordx4 v[146:147], v[142:145], off offset:16

.LBB0_446:
	s_and_b64 vcc, exec, s[54:55]
	s_waitcnt vmcnt(1)
	v_sub_f32_e32 v170, 1.0, v134
	s_waitcnt vmcnt(0)
	s_mov_b32 s100, 1
	v_sub_f32_e32 v169, 1.0, v130
	v_sub_f32_e32 v168, 1.0, v135
	v_sub_f32_e32 v167, 1.0, v131
	v_sub_f32_e32 v166, 1.0, v136
	v_sub_f32_e32 v164, 1.0, v132
	v_sub_f32_e32 v163, 1.0, v137
	v_sub_f32_e32 v162, 1.0, v133
	s_cbranch_vccz .LBB0_468
	v_mul_f32_e32 v139, 0xbfb8aa3b, v106
	v_exp_f32_e32 v139, v139
	v_mul_f32_e32 v140, 0xbfb8aa3b, v111
	v_exp_f32_e32 v140, v140
	v_mul_f32_e32 v141, 0xbfb8aa3b, v112
	v_add_f32_e32 v139, 1.0, v139
	v_rcp_f32_e32 v139, v139
	v_add_f32_e32 v140, 1.0, v140
	v_rcp_f32_e32 v140, v140
	v_exp_f32_e32 v141, v141
	v_fma_f32 v139, v139, v169, v130
	v_log_f32_e32 v142, v139
	v_fma_f32 v139, v140, v168, v135
	v_mul_f32_e32 v140, 0xbfb8aa3b, v107
	v_exp_f32_e32 v140, v140
	v_add_f32_e32 v141, 1.0, v141
	v_mul_f32_e32 v143, 0xbfb8aa3b, v108
	v_rcp_f32_e32 v141, v141
	v_add_f32_e32 v140, 1.0, v140
	v_rcp_f32_e32 v140, v140
	v_exp_f32_e32 v143, v143
	v_mul_f32_e32 v138, 0xbfb8aa3b, v110
	v_exp_f32_e32 v138, v138
	v_fma_f32 v171, v140, v167, v131
	v_fma_f32 v140, v141, v166, v136
	v_add_f32_e32 v141, 1.0, v143
	v_mul_f32_e32 v143, 0xbfb8aa3b, v113
	v_exp_f32_e32 v143, v143
	v_mul_f32_e32 v144, 0xbfb8aa3b, v109
	v_exp_f32_e32 v144, v144
	v_add_f32_e32 v138, 1.0, v138
	v_rcp_f32_e32 v141, v141
	v_add_f32_e32 v143, 1.0, v143
	v_rcp_f32_e32 v138, v138
	v_rcp_f32_e32 v143, v143
	v_add_f32_e32 v144, 1.0, v144
	v_rcp_f32_e32 v145, v144
	v_fma_f32 v141, v141, v164, v132
	v_fma_f32 v138, v138, v170, v134
	v_log_f32_e32 v144, v141
	v_fma_f32 v141, v143, v163, v137
	v_log_f32_e32 v138, v138
	v_log_f32_e32 v139, v139
	v_log_f32_e32 v140, v140
	v_log_f32_e32 v141, v141
	v_fma_f32 v143, v145, v162, v133
	v_log_f32_e32 v145, v143
	v_log_f32_e32 v143, v171
	v_or_b32_e32 v148, v148, v165
	v_pk_mul_f32 v[140:141], v[140:141], s[96:97] op_sel_hi:[1,0]
	v_pk_mul_f32 v[138:139], v[138:139], s[96:97] op_sel_hi:[1,0]
	v_lshl_add_u64 v[148:149], v[148:149], 2, s[28:29]
	v_pk_mul_f32 v[144:145], v[144:145], s[96:97] op_sel_hi:[1,0]
	v_pk_mul_f32 v[142:143], v[142:143], s[96:97] op_sel_hi:[1,0]
	global_store_dwordx4 v[148:149], v[138:141], off
	global_store_dwordx4 v[148:149], v[142:145], off offset:16
	s_and_b64 vcc, exec, s[50:51]
	s_mov_b64 s[54:55], -1
	s_cbranch_vccz .LBB0_469

.LBB0_627:
	s_mov_b32 s100, 0
	v_readlane_b32 s0, v247, 59
	v_readlane_b32 s6, v246, 1
	v_readlane_b32 s1, v247, 60
	v_readlane_b32 s2, v247, 61
	v_readlane_b32 s3, v247, 62
	v_readlane_b32 s4, v247, 63
	v_readlane_b32 s5, v246, 0
	v_readlane_b32 s7, v246, 2
	s_add_i32 s6, s6, 1
	v_writelane_b32 v247, s0, 59
	s_cmp_ge_i32 s6, s7
	s_nop 0
	v_writelane_b32 v247, s1, 60
	v_writelane_b32 v246, s5, 0
	v_writelane_b32 v247, s2, 61
	v_writelane_b32 v246, s6, 1
	v_writelane_b32 v247, s3, 62
	v_writelane_b32 v246, s7, 2
	s_mov_b64 s[0:1], -1
	v_writelane_b32 v247, s4, 63
	s_cbranch_scc0 .LBB0_628
	s_getpc_b64 s[98:99]
